# v18 plus rstd row-stat loads of the in_proj GEMM epilogue hoisted above the K loop
# baseline (speedup 1.0000x reference)
; #define PG8_STAGE(bufoff, gbase, voff) do { _Pragma("unroll") for (int _i = 0; _i < 2; ++_i) \
;         __builtin_amdgcn_global_load_lds((const unsigned*)((const char*)(gbase) + (voff)[_i]), (LAS unsigned*)(lds + (bufoff) + ldsw + _i * 8192), 16, 0, 0); } while (0)
; #define PG8_WAIT_V(n) asm volatile("s_waitcnt vmcnt(" #n ")" ::: "memory")
; #define PG8_BAR __builtin_amdgcn_s_barrier()
;     DI void prep(const Unit& u, int tid) const { if (tid < 256) *(LAS f32x4*)(tbl + (u.ui & 1) * 4096 + tid * 16) = factors(u.r0 + tid); }
; template <class Epi, bool ALIGN_EPI>
; DI void gemm_phase(lptr lds, const Gemm g, const StaticOrder& S, const Epi& E) {
;     ...
;     const char* cA = (const char*)g.A + (size_t)cur.pm * tstepA; const char* cB = (const char*)g.Bt + (size_t)cur.pn * tstepB;
;     if constexpr (Epi::RESCALE) E.prep(cur, tid);
;     PG8_STAGE(PG8_SB(0, 0), cB, voffB); PG8_STAGE(PG8_SB(0, 1), cB + hstepB, voffB); PG8_STAGE(PG8_SA(0, 0), cA, voffA); PG8_STAGE(PG8_SA(0, 1), cA + hstepA, voffA);
;     if (wr == 1) PG8_BAR;
;     PG8_WAIT_V(2); PG8_BAR;
;     PG8_STAGE(PG8_SB(1, 0), cB + kstep, voffB); PG8_STAGE(PG8_SA(1, 0), cA + kstep, voffA); PG8_STAGE(PG8_SB(1, 1), cB + hstepB + kstep, voffB);
;     PG8_WAIT_V(6); PG8_BAR;
;     for (;;) {
;         const bool has_next = S.next(ui + 1, nxt);
;         const char* nA = has_next ? (const char*)g.A + (size_t)nxt.pm * tstepA : cA; const char* nB = has_next ? (const char*)g.Bt + (size_t)nxt.pn * tstepB : cB;
;     template <int NAI> DI void run(AccRef acc, const Unit& u, int wr, int wc, int fr, int fq) const {
;     ...
;             for (int m = 0; m < 4; ++m) rsv[ai][m] = rstd[EPI_ROW(ai, m)];
.LBB0_224:
	s_ashr_i32 s23, s22, 31
	s_lshl_b64 s[24:25], s[22:23], 19
	s_add_u32 s24, s92, s24
	s_addc_u32 s25, s93, s25
	s_and_b64 s[26:27], s[2:3], exec
	s_cselect_b32 s23, s25, s5
	s_cselect_b32 s31, s24, s4
	s_ashr_i32 s21, s20, 31
	s_lshl_b64 s[26:27], s[20:21], 19
	s_add_u32 s26, s19, s26
	s_addc_u32 s27, s40, s27
	s_and_b64 s[28:29], s[2:3], exec
	s_cselect_b32 s21, s27, s7
	s_cselect_b32 s33, s26, s6
	s_add_u32 s4, s4, 0x40080
	s_addc_u32 s5, s5, 0
	s_add_u32 s35, s6, 0x100
	v_mov_b32_e32 v0, 0
	s_addc_u32 s36, s7, 0
	s_mov_b32 s37, -2
	v_mov_b32_e32 v1, v0
	v_mov_b32_e32 v2, v0
	v_mov_b32_e32 v3, v0
	v_mov_b32_e32 v4, v0
	v_mov_b32_e32 v5, v0
	v_mov_b32_e32 v6, v0
	v_mov_b32_e32 v7, v0
	v_mov_b32_e32 v16, v0
	v_mov_b32_e32 v17, v0
	v_mov_b32_e32 v18, v0
	v_mov_b32_e32 v19, v0
	v_mov_b32_e32 v20, v0
	v_mov_b32_e32 v21, v0
	v_mov_b32_e32 v22, v0
	v_mov_b32_e32 v23, v0
	v_mov_b32_e32 v32, v0
	v_mov_b32_e32 v33, v0
	v_mov_b32_e32 v34, v0
	v_mov_b32_e32 v35, v0
	v_mov_b32_e32 v36, v0
	v_mov_b32_e32 v37, v0
	v_mov_b32_e32 v38, v0
	v_mov_b32_e32 v39, v0
	v_mov_b32_e32 v48, v0
	v_mov_b32_e32 v49, v0
	v_mov_b32_e32 v50, v0
	v_mov_b32_e32 v51, v0
	v_mov_b32_e32 v52, v0
	v_mov_b32_e32 v53, v0
	v_mov_b32_e32 v54, v0
	v_mov_b32_e32 v55, v0
	v_mov_b32_e32 v8, v0
	v_mov_b32_e32 v9, v0
	v_mov_b32_e32 v10, v0
	v_mov_b32_e32 v11, v0
	v_mov_b32_e32 v12, v0
	v_mov_b32_e32 v13, v0
	v_mov_b32_e32 v14, v0
	v_mov_b32_e32 v15, v0
	v_mov_b32_e32 v24, v0
	v_mov_b32_e32 v25, v0
	v_mov_b32_e32 v26, v0
	v_mov_b32_e32 v27, v0
	v_mov_b32_e32 v28, v0
	v_mov_b32_e32 v29, v0
	v_mov_b32_e32 v30, v0
	v_mov_b32_e32 v31, v0
	v_mov_b32_e32 v40, v0
	v_mov_b32_e32 v41, v0
	v_mov_b32_e32 v42, v0
	v_mov_b32_e32 v43, v0
	v_mov_b32_e32 v44, v0
	v_mov_b32_e32 v45, v0
	v_mov_b32_e32 v46, v0
	v_mov_b32_e32 v47, v0
	v_mov_b32_e32 v56, v0
	v_mov_b32_e32 v57, v0
	v_mov_b32_e32 v58, v0
	v_mov_b32_e32 v59, v0
	v_mov_b32_e32 v60, v0
	v_mov_b32_e32 v61, v0
	v_mov_b32_e32 v62, v0
	v_mov_b32_e32 v63, v0
	v_mov_b32_e32 v64, v0
	v_mov_b32_e32 v65, v0
	v_mov_b32_e32 v66, v0
	v_mov_b32_e32 v67, v0
	v_mov_b32_e32 v68, v0
	v_mov_b32_e32 v69, v0
	v_mov_b32_e32 v70, v0
	v_mov_b32_e32 v71, v0
	v_mov_b32_e32 v80, v0
	v_mov_b32_e32 v81, v0
	v_mov_b32_e32 v82, v0
	v_mov_b32_e32 v83, v0
	v_mov_b32_e32 v84, v0
	v_mov_b32_e32 v85, v0
	v_mov_b32_e32 v86, v0
	v_mov_b32_e32 v87, v0
	v_mov_b32_e32 v96, v0
	v_mov_b32_e32 v97, v0
	v_mov_b32_e32 v98, v0
	v_mov_b32_e32 v99, v0
	v_mov_b32_e32 v100, v0
	v_mov_b32_e32 v101, v0
	v_mov_b32_e32 v102, v0
	v_mov_b32_e32 v103, v0
	v_mov_b32_e32 v112, v0
	v_mov_b32_e32 v113, v0
	v_mov_b32_e32 v114, v0
	v_mov_b32_e32 v115, v0
	v_mov_b32_e32 v116, v0
	v_mov_b32_e32 v117, v0
	v_mov_b32_e32 v118, v0
	v_mov_b32_e32 v119, v0
	v_mov_b32_e32 v72, v0
	v_mov_b32_e32 v73, v0
	v_mov_b32_e32 v74, v0
	v_mov_b32_e32 v75, v0
	v_mov_b32_e32 v76, v0
	v_mov_b32_e32 v77, v0
	v_mov_b32_e32 v78, v0
	v_mov_b32_e32 v79, v0
	v_mov_b32_e32 v88, v0
	v_mov_b32_e32 v89, v0
	v_mov_b32_e32 v90, v0
	v_mov_b32_e32 v91, v0
	v_mov_b32_e32 v92, v0
	v_mov_b32_e32 v93, v0
	v_mov_b32_e32 v94, v0
	v_mov_b32_e32 v95, v0
	v_mov_b32_e32 v104, v0
	v_mov_b32_e32 v105, v0
	v_mov_b32_e32 v106, v0
	v_mov_b32_e32 v107, v0
	v_mov_b32_e32 v108, v0
	v_mov_b32_e32 v109, v0
	v_mov_b32_e32 v110, v0
	v_mov_b32_e32 v111, v0
	v_mov_b32_e32 v120, v0
	v_mov_b32_e32 v121, v0
	v_mov_b32_e32 v122, v0
	v_mov_b32_e32 v123, v0
	v_mov_b32_e32 v124, v0
	v_mov_b32_e32 v125, v0
	v_mov_b32_e32 v126, v0
	v_mov_b32_e32 v127, v0
	s_waitcnt vmcnt(0)
	v_add_u32_e32 v255, s30, v208
	v_lshlrev_b32_e32 v255, 2, v255
	global_load_dword v246, v255, s[10:11]
	global_load_dword v247, v255, s[10:11] offset:64
	global_load_dword v248, v255, s[10:11] offset:128
	global_load_dword v249, v255, s[10:11] offset:192
	global_load_dword v250, v255, s[10:11] offset:512
	global_load_dword v251, v255, s[10:11] offset:576
	global_load_dword v252, v255, s[10:11] offset:640
	global_load_dword v253, v255, s[10:11] offset:704

;     template <int NAI> DI void run(AccRef acc, const Unit& u, int wr, int wc, int fr, int fq) const {
;     ...
;         bf16_t* const gbase = pn < 20 ? P + (size_t)(pn >> 2) * GSZ + (pn & 3) * 256 : pn == 20 ? P + G_SKV : P + G_GA + (size_t)((pn - 21) >> 2) * GSZ + ((pn - 21) & 3) * 256;
;         const unsigned pitch = pn == 20 ? 256u : 1024u;
;         float rsv[2][4];
; #pragma unroll
;         for (int ai = 0; ai < NAI; ++ai)
; #pragma unroll
;             for (int m = 0; m < 4; ++m) rsv[ai][m] = rstd[EPI_ROW(ai, m)];
; #pragma unroll
;         for (int ai = 0; ai < NAI; ++ai) {
;             if (pn < 8) {
;                 u32x4 cs[4][2];
; #pragma unroll
;                 for (int m = 0; m < 4; ++m) { const int row = EPI_ROW(ai, m); const int pos = row < MP ? (row & (SEQ - 1)) : (SEQ + ((row - MP) & 63));
;                     const unsigned* tp = rope + pos * 128 + cl; cs[m][0] = *(const u32x4*)tp; cs[m][1] = *(const u32x4*)(tp + 4); }
; #pragma unroll
;                 for (int m = 0; m < 4; ++m) { const int row = EPI_ROW(ai, m); bf16_t* prow = gbase + ((unsigned)row * pitch + (unsigned)cl);
;                     const float sc = pn >= 4 ? rsv[ai][m] * 0.0625f : rsv[ai][m];
;                     const u32x4 w0 = cs[m][0], w1 = cs[m][1];
;                     const f32x4 c0 = (f32x4){f16lo(w0.x), f16lo(w0.y), f16lo(w0.z), f16lo(w0.w)}, s0 = (f32x4){f16hi(w0.x), f16hi(w0.y), f16hi(w0.z), f16hi(w0.w)};
;                     const f32x4 c1 = (f32x4){f16lo(w1.x), f16lo(w1.y), f16lo(w1.z), f16lo(w1.w)}, s1 = (f32x4){f16hi(w1.x), f16hi(w1.y), f16hi(w1.z), f16hi(w1.w)};
;                     const f32x4 x10 = acc[ai][0][m][0] * sc, x11 = acc[ai][0][m][1] * sc, x20 = acc[ai][1][m][0] * sc, x21 = acc[ai][1][m][1] * sc;
;                     st8(prow, x10 * c0 - x20 * s0, x11 * c1 - x21 * s1);
;                     st8(prow + 128, x20 * c0 + x10 * s0, x21 * c1 + x11 * s1); }
;             } else {
; #pragma unroll
;                 for (int m = 0; m < 4; ++m) { const int row = EPI_ROW(ai, m); bf16_t* prow = gbase + ((unsigned)row * pitch + (unsigned)cl); const float rs = rsv[ai][m];
; #pragma unroll
;                     for (int bj = 0; bj < 2; ++bj) {
;                         f32x4 a = acc[ai][bj][m][0] * rs, b = acc[ai][bj][m][1] * rs;
;                         if (pn >= 12 && pn < 16) { a = a * sigm4(a); b = b * sigm4(b); }
.LBB0_230:
	v_add_u32_e32 v174, s30, v208
	v_add_u32_e32 v176, 16, v174
	v_add_u32_e32 v170, 32, v174
	v_add_u32_e32 v166, 48, v174
	v_ashrrev_i32_e32 v175, 31, v174
	v_ashrrev_i32_e32 v177, 31, v176
	v_ashrrev_i32_e32 v171, 31, v170
	v_ashrrev_i32_e32 v167, 31, v166
	v_add_u32_e32 v158, 0x80, v174
	v_add_u32_e32 v160, 0x90, v174
	v_add_u32_e32 v154, 0xa0, v174
	v_add_u32_e32 v148, 0xb0, v174
	v_lshl_add_u64 v[150:151], v[174:175], 2, s[10:11]
	v_lshl_add_u64 v[156:157], v[176:177], 2, s[10:11]
	v_lshl_add_u64 v[162:163], v[170:171], 2, s[10:11]
	v_lshl_add_u64 v[164:165], v[166:167], 2, s[10:11]
	v_ashrrev_i32_e32 v159, 31, v158
	v_ashrrev_i32_e32 v161, 31, v160
	v_ashrrev_i32_e32 v155, 31, v154
	v_ashrrev_i32_e32 v149, 31, v148
	v_lshl_add_u64 v[182:183], v[158:159], 2, s[10:11]
	v_lshl_add_u64 v[184:185], v[160:161], 2, s[10:11]
	v_lshl_add_u64 v[186:187], v[154:155], 2, s[10:11]
	v_lshl_add_u64 v[188:189], v[148:149], 2, s[10:11]
	v_mov_b32_e32 v180, v246
	v_mov_b32_e32 v178, v247
	v_mov_b32_e32 v172, v248
	v_mov_b32_e32 v168, v249
	s_nop 0
	v_mov_b32_e32 v164, v250
	v_mov_b32_e32 v162, v251
	v_mov_b32_e32 v156, v252
	v_mov_b32_e32 v150, v253
	s_cmp_gt_i32 s34, 7
	s_cselect_b64 s[30:31], -1, 0
	s_cmp_eq_u32 s34, 20
	s_cselect_b32 s23, 8, 10
	s_and_b32 s21, s34, 0x7ffffffc
	s_cmp_gt_i32 s34, 20
	s_cselect_b64 s[6:7], -1, 0
	s_cmp_gt_i32 s34, 3
	s_cselect_b64 s[4:5], -1, 0
	s_cmp_lt_i32 s34, 8
	s_mov_b64 s[34:35], -1
	s_cbranch_scc1 .LBB0_272
	s_cmp_eq_u32 s21, 12
	s_cbranch_scc1 .Lipe_silu
	s_cmp_eq_u32 s21, 16
	s_cbranch_scc1 .Lipe_s125
	s_and_b64 vcc, exec, s[6:7]
	s_cbranch_vccnz .Lipe_sigm
	v_lshl_or_b32 v136, v174, s23, v210
	v_lshl_add_u64 v[182:183], v[136:137], 1, s[28:29]
	v_pk_mul_f32 v[124:125], v[124:125], v[180:181] op_sel_hi:[1,0]
	v_pk_mul_f32 v[126:127], v[126:127], v[180:181] op_sel_hi:[1,0]
	v_pk_mul_f32 v[120:121], v[120:121], v[180:181] op_sel_hi:[1,0]
	v_pk_mul_f32 v[122:123], v[122:123], v[180:181] op_sel_hi:[1,0]
	v_cvt_pk_bf16_f32 v186, v124, v125
	v_cvt_pk_bf16_f32 v187, v126, v127
	v_cvt_pk_bf16_f32 v188, v120, v121
	v_cvt_pk_bf16_f32 v189, v122, v123
	global_store_dwordx4 v[182:183], v[186:189], off
	v_pk_mul_f32 v[116:117], v[116:117], v[180:181] op_sel_hi:[1,0]
	v_pk_mul_f32 v[118:119], v[118:119], v[180:181] op_sel_hi:[1,0]
	v_pk_mul_f32 v[112:113], v[112:113], v[180:181] op_sel_hi:[1,0]
	v_pk_mul_f32 v[114:115], v[114:115], v[180:181] op_sel_hi:[1,0]
	v_cvt_pk_bf16_f32 v190, v116, v117
	v_cvt_pk_bf16_f32 v191, v118, v119
	v_cvt_pk_bf16_f32 v192, v112, v113
	v_cvt_pk_bf16_f32 v193, v114, v115
	global_store_dwordx4 v[182:183], v[190:193], off offset:256
	v_lshl_or_b32 v136, v176, s23, v210
	v_lshl_add_u64 v[184:185], v[136:137], 1, s[28:29]
	v_pk_mul_f32 v[108:109], v[108:109], v[178:179] op_sel_hi:[1,0]
	v_pk_mul_f32 v[110:111], v[110:111], v[178:179] op_sel_hi:[1,0]
	v_pk_mul_f32 v[104:105], v[104:105], v[178:179] op_sel_hi:[1,0]
	v_pk_mul_f32 v[106:107], v[106:107], v[178:179] op_sel_hi:[1,0]
	v_cvt_pk_bf16_f32 v186, v108, v109
	v_cvt_pk_bf16_f32 v187, v110, v111
	v_cvt_pk_bf16_f32 v188, v104, v105
	v_cvt_pk_bf16_f32 v189, v106, v107
	global_store_dwordx4 v[184:185], v[186:189], off
	v_pk_mul_f32 v[100:101], v[100:101], v[178:179] op_sel_hi:[1,0]
	v_pk_mul_f32 v[102:103], v[102:103], v[178:179] op_sel_hi:[1,0]
	v_pk_mul_f32 v[96:97], v[96:97], v[178:179] op_sel_hi:[1,0]
	v_pk_mul_f32 v[98:99], v[98:99], v[178:179] op_sel_hi:[1,0]
	v_cvt_pk_bf16_f32 v190, v100, v101
	v_cvt_pk_bf16_f32 v191, v102, v103
	v_cvt_pk_bf16_f32 v192, v96, v97
	v_cvt_pk_bf16_f32 v193, v98, v99
	global_store_dwordx4 v[184:185], v[190:193], off offset:256
	v_lshl_or_b32 v136, v170, s23, v210
	v_lshl_add_u64 v[182:183], v[136:137], 1, s[28:29]
	v_pk_mul_f32 v[92:93], v[92:93], v[172:173] op_sel_hi:[1,0]
	v_pk_mul_f32 v[94:95], v[94:95], v[172:173] op_sel_hi:[1,0]
	v_pk_mul_f32 v[88:89], v[88:89], v[172:173] op_sel_hi:[1,0]
	v_pk_mul_f32 v[90:91], v[90:91], v[172:173] op_sel_hi:[1,0]
	v_cvt_pk_bf16_f32 v186, v92, v93
	v_cvt_pk_bf16_f32 v187, v94, v95
	v_cvt_pk_bf16_f32 v188, v88, v89
	v_cvt_pk_bf16_f32 v189, v90, v91
	global_store_dwordx4 v[182:183], v[186:189], off
	v_pk_mul_f32 v[84:85], v[84:85], v[172:173] op_sel_hi:[1,0]
	v_pk_mul_f32 v[86:87], v[86:87], v[172:173] op_sel_hi:[1,0]
	v_pk_mul_f32 v[80:81], v[80:81], v[172:173] op_sel_hi:[1,0]
	v_pk_mul_f32 v[82:83], v[82:83], v[172:173] op_sel_hi:[1,0]
	v_cvt_pk_bf16_f32 v190, v84, v85
	v_cvt_pk_bf16_f32 v191, v86, v87
	v_cvt_pk_bf16_f32 v192, v80, v81
	v_cvt_pk_bf16_f32 v193, v82, v83
	global_store_dwordx4 v[182:183], v[190:193], off offset:256
	v_lshl_or_b32 v136, v166, s23, v210
	v_lshl_add_u64 v[184:185], v[136:137], 1, s[28:29]
; DI void st8(bf16_t* p, f32x4 a, f32x4 b) { u32x4 w; w.x = cvt_pk_bf16(a.x, a.y); w.y = cvt_pk_bf16(a.z, a.w); w.z = cvt_pk_bf16(b.x, b.y); w.w = cvt_pk_bf16(b.z, b.w); *(u32x4*)p = w; }
; DI f32x4 sigm4(f32x4 v) { f32x4 r; r.x = sigm(v.x); r.y = sigm(v.y); r.z = sigm(v.z); r.w = sigm(v.w); return r; }
;     template <int NAI> DI void run(AccRef acc, const Unit& u, int wr, int wc, int fr, int fq) const {
;     ...
;                 for (int m = 0; m < 4; ++m) { const int row = EPI_ROW(ai, m); bf16_t* prow = gbase + ((unsigned)row * pitch + (unsigned)cl); const float rs = rsv[ai][m];
; #pragma unroll
;                     for (int bj = 0; bj < 2; ++bj) {
;                         f32x4 a = acc[ai][bj][m][0] * rs, b = acc[ai][bj][m][1] * rs;
;                         if (pn >= 12 && pn < 16) { a = a * sigm4(a); b = b * sigm4(b); }
;                         else if (pn >= 16 && pn < 20) { a = a * 0.125f; b = b * 0.125f; }
;                         else if (pn >= 21) { a = sigm4(a); b = sigm4(b); }
;                         st8(prow + bj * 128, a, b);
	v_pk_mul_f32 v[76:77], v[76:77], v[168:169] op_sel_hi:[1,0]
	v_pk_mul_f32 v[78:79], v[78:79], v[168:169] op_sel_hi:[1,0]
	v_pk_mul_f32 v[72:73], v[72:73], v[168:169] op_sel_hi:[1,0]
	v_pk_mul_f32 v[74:75], v[74:75], v[168:169] op_sel_hi:[1,0]
	v_cvt_pk_bf16_f32 v186, v76, v77
	v_cvt_pk_bf16_f32 v187, v78, v79
	v_cvt_pk_bf16_f32 v188, v72, v73
	v_cvt_pk_bf16_f32 v189, v74, v75
	global_store_dwordx4 v[184:185], v[186:189], off
	v_pk_mul_f32 v[68:69], v[68:69], v[168:169] op_sel_hi:[1,0]
	v_pk_mul_f32 v[70:71], v[70:71], v[168:169] op_sel_hi:[1,0]
	v_pk_mul_f32 v[64:65], v[64:65], v[168:169] op_sel_hi:[1,0]
	v_pk_mul_f32 v[66:67], v[66:67], v[168:169] op_sel_hi:[1,0]
	v_cvt_pk_bf16_f32 v190, v68, v69
	v_cvt_pk_bf16_f32 v191, v70, v71
	v_cvt_pk_bf16_f32 v192, v64, v65
	v_cvt_pk_bf16_f32 v193, v66, v67
	global_store_dwordx4 v[184:185], v[190:193], off offset:256
	v_lshl_or_b32 v136, v158, s23, v210
	v_lshl_add_u64 v[182:183], v[136:137], 1, s[28:29]
	v_pk_mul_f32 v[60:61], v[60:61], v[164:165] op_sel_hi:[1,0]
	v_pk_mul_f32 v[62:63], v[62:63], v[164:165] op_sel_hi:[1,0]
	v_pk_mul_f32 v[56:57], v[56:57], v[164:165] op_sel_hi:[1,0]
	v_pk_mul_f32 v[58:59], v[58:59], v[164:165] op_sel_hi:[1,0]
	v_cvt_pk_bf16_f32 v186, v60, v61
	v_cvt_pk_bf16_f32 v187, v62, v63
	v_cvt_pk_bf16_f32 v188, v56, v57
	v_cvt_pk_bf16_f32 v189, v58, v59
	global_store_dwordx4 v[182:183], v[186:189], off
	v_pk_mul_f32 v[52:53], v[52:53], v[164:165] op_sel_hi:[1,0]
	v_pk_mul_f32 v[54:55], v[54:55], v[164:165] op_sel_hi:[1,0]
	v_pk_mul_f32 v[48:49], v[48:49], v[164:165] op_sel_hi:[1,0]
	v_pk_mul_f32 v[50:51], v[50:51], v[164:165] op_sel_hi:[1,0]
	v_cvt_pk_bf16_f32 v190, v52, v53
	v_cvt_pk_bf16_f32 v191, v54, v55
	v_cvt_pk_bf16_f32 v192, v48, v49
	v_cvt_pk_bf16_f32 v193, v50, v51
	global_store_dwordx4 v[182:183], v[190:193], off offset:256
	v_lshl_or_b32 v136, v160, s23, v210
	v_lshl_add_u64 v[184:185], v[136:137], 1, s[28:29]
	v_pk_mul_f32 v[44:45], v[44:45], v[162:163] op_sel_hi:[1,0]
	v_pk_mul_f32 v[46:47], v[46:47], v[162:163] op_sel_hi:[1,0]
	v_pk_mul_f32 v[40:41], v[40:41], v[162:163] op_sel_hi:[1,0]
	v_pk_mul_f32 v[42:43], v[42:43], v[162:163] op_sel_hi:[1,0]
	v_cvt_pk_bf16_f32 v186, v44, v45
	v_cvt_pk_bf16_f32 v187, v46, v47
	v_cvt_pk_bf16_f32 v188, v40, v41
	v_cvt_pk_bf16_f32 v189, v42, v43
	global_store_dwordx4 v[184:185], v[186:189], off
	v_pk_mul_f32 v[36:37], v[36:37], v[162:163] op_sel_hi:[1,0]
	v_pk_mul_f32 v[38:39], v[38:39], v[162:163] op_sel_hi:[1,0]
	v_pk_mul_f32 v[32:33], v[32:33], v[162:163] op_sel_hi:[1,0]
	v_pk_mul_f32 v[34:35], v[34:35], v[162:163] op_sel_hi:[1,0]
	v_cvt_pk_bf16_f32 v190, v36, v37
	v_cvt_pk_bf16_f32 v191, v38, v39
	v_cvt_pk_bf16_f32 v192, v32, v33
	v_cvt_pk_bf16_f32 v193, v34, v35
	global_store_dwordx4 v[184:185], v[190:193], off offset:256
	v_lshl_or_b32 v136, v154, s23, v210
	v_lshl_add_u64 v[182:183], v[136:137], 1, s[28:29]
	v_pk_mul_f32 v[28:29], v[28:29], v[156:157] op_sel_hi:[1,0]
	v_pk_mul_f32 v[30:31], v[30:31], v[156:157] op_sel_hi:[1,0]
	v_pk_mul_f32 v[24:25], v[24:25], v[156:157] op_sel_hi:[1,0]
	v_pk_mul_f32 v[26:27], v[26:27], v[156:157] op_sel_hi:[1,0]
	v_cvt_pk_bf16_f32 v186, v28, v29
	v_cvt_pk_bf16_f32 v187, v30, v31
	v_cvt_pk_bf16_f32 v188, v24, v25
	v_cvt_pk_bf16_f32 v189, v26, v27
	global_store_dwordx4 v[182:183], v[186:189], off
	v_pk_mul_f32 v[20:21], v[20:21], v[156:157] op_sel_hi:[1,0]
	v_pk_mul_f32 v[22:23], v[22:23], v[156:157] op_sel_hi:[1,0]
	v_pk_mul_f32 v[16:17], v[16:17], v[156:157] op_sel_hi:[1,0]
	v_pk_mul_f32 v[18:19], v[18:19], v[156:157] op_sel_hi:[1,0]
	v_cvt_pk_bf16_f32 v190, v20, v21
	v_cvt_pk_bf16_f32 v191, v22, v23
	v_cvt_pk_bf16_f32 v192, v16, v17
	v_cvt_pk_bf16_f32 v193, v18, v19
	global_store_dwordx4 v[182:183], v[190:193], off offset:256
	v_lshl_or_b32 v136, v148, s23, v210
	v_lshl_add_u64 v[184:185], v[136:137], 1, s[28:29]
	v_pk_mul_f32 v[12:13], v[12:13], v[150:151] op_sel_hi:[1,0]
	v_pk_mul_f32 v[14:15], v[14:15], v[150:151] op_sel_hi:[1,0]
	v_pk_mul_f32 v[8:9], v[8:9], v[150:151] op_sel_hi:[1,0]
	v_pk_mul_f32 v[10:11], v[10:11], v[150:151] op_sel_hi:[1,0]
	v_cvt_pk_bf16_f32 v186, v12, v13
	v_cvt_pk_bf16_f32 v187, v14, v15
	v_cvt_pk_bf16_f32 v188, v8, v9
	v_cvt_pk_bf16_f32 v189, v10, v11
	global_store_dwordx4 v[184:185], v[186:189], off
	v_pk_mul_f32 v[4:5], v[4:5], v[150:151] op_sel_hi:[1,0]
	v_pk_mul_f32 v[6:7], v[6:7], v[150:151] op_sel_hi:[1,0]
	v_pk_mul_f32 v[0:1], v[0:1], v[150:151] op_sel_hi:[1,0]
	v_pk_mul_f32 v[2:3], v[2:3], v[150:151] op_sel_hi:[1,0]
	v_cvt_pk_bf16_f32 v190, v4, v5
	v_cvt_pk_bf16_f32 v191, v6, v7
	v_cvt_pk_bf16_f32 v192, v0, v1
	v_cvt_pk_bf16_f32 v193, v2, v3
	global_store_dwordx4 v[184:185], v[190:193], off offset:256
	s_branch .LBB0_275

; __global__ void __launch_bounds__(512, 2) fwd_mega(Params p) {
	.amdhsa_kernel _Z8fwd_mega6Params
		.amdhsa_group_segment_fixed_size 0
		.amdhsa_private_segment_fixed_size 0
		.amdhsa_kernarg_size 488
		.amdhsa_user_sgpr_count 2
		.amdhsa_user_sgpr_dispatch_ptr 0
		.amdhsa_user_sgpr_queue_ptr 0
		.amdhsa_user_sgpr_kernarg_segment_ptr 1
		.amdhsa_user_sgpr_dispatch_id 0
		.amdhsa_user_sgpr_kernarg_preload_length 0
		.amdhsa_user_sgpr_kernarg_preload_offset 0
		.amdhsa_user_sgpr_private_segment_size 0
		.amdhsa_uses_dynamic_stack 0
		.amdhsa_enable_private_segment 0
		.amdhsa_system_sgpr_workgroup_id_x 1
		.amdhsa_system_sgpr_workgroup_id_y 0
		.amdhsa_system_sgpr_workgroup_id_z 0
		.amdhsa_system_sgpr_workgroup_info 0
		.amdhsa_system_vgpr_workitem_id 2
		.amdhsa_next_free_vgpr 256
		.amdhsa_next_free_sgpr 99
		.amdhsa_accum_offset 256
		.amdhsa_reserve_vcc 1
		.amdhsa_float_round_mode_32 0
		.amdhsa_float_round_mode_16_64 0
		.amdhsa_float_denorm_mode_32 3
		.amdhsa_float_denorm_mode_16_64 3
		.amdhsa_dx10_clamp 1
		.amdhsa_ieee_mode 1
		.amdhsa_fp16_overflow 0
		.amdhsa_tg_split 0
		.amdhsa_exception_fp_ieee_invalid_op 0
		.amdhsa_exception_fp_denorm_src 0
		.amdhsa_exception_fp_ieee_div_zero 0
		.amdhsa_exception_fp_ieee_overflow 0
		.amdhsa_exception_fp_ieee_underflow 0
		.amdhsa_exception_fp_ieee_inexact 0
		.amdhsa_exception_int_div_zero 0
	.end_amdhsa_kernel

; __global__ void __launch_bounds__(512, 2) fwd_mega(Params p) {
amdhsa.kernels:
  - .agpr_count:     0
    .args:
      - .offset:         0
        .size:           232
        .value_kind:     by_value
      - .offset:         232
        .size:           4
        .value_kind:     hidden_block_count_x
      - .offset:         236
        .size:           4
        .value_kind:     hidden_block_count_y
      - .offset:         240
        .size:           4
        .value_kind:     hidden_block_count_z
      - .offset:         244
        .size:           2
        .value_kind:     hidden_group_size_x
      - .offset:         246
        .size:           2
        .value_kind:     hidden_group_size_y
      - .offset:         248
        .size:           2
        .value_kind:     hidden_group_size_z
      - .offset:         250
        .size:           2
        .value_kind:     hidden_remainder_x
      - .offset:         252
        .size:           2
        .value_kind:     hidden_remainder_y
      - .offset:         254
        .size:           2
        .value_kind:     hidden_remainder_z
      - .offset:         272
        .size:           8
        .value_kind:     hidden_global_offset_x
      - .offset:         280
        .size:           8
        .value_kind:     hidden_global_offset_y
      - .offset:         288
        .size:           8
        .value_kind:     hidden_global_offset_z
      - .offset:         296
        .size:           2
        .value_kind:     hidden_grid_dims
      - .offset:         320
        .size:           8
        .value_kind:     hidden_multigrid_sync_arg
      - .offset:         352
        .size:           4
        .value_kind:     hidden_dynamic_lds_size
    .group_segment_fixed_size: 0
    .kernarg_segment_align: 8
    .kernarg_segment_size: 488
    .language:       OpenCL C
    .language_version:
      - 2
      - 0
    .max_flat_workgroup_size: 512
    .name:           _Z8fwd_mega6Params
    .private_segment_fixed_size: 0
    .sgpr_count:     105
    .sgpr_spill_count: 35
    .symbol:         _Z8fwd_mega6Params.kd
    .uniform_work_group_size: 1
    .uses_dynamic_stack: false
    .vgpr_count:     256
    .vgpr_spill_count: 0
    .wavefront_size: 64
